# windowed attention: running row max folded into the score MFMA accumulator init (C = -m), removing 48 v_sub per 64-key half tile; rescale path adjusts scores instead
# baseline (speedup 1.0000x reference)
;     __device__ __forceinline__ const float* in(int i) const { return (const float*)(const __attribute__((address_space(1))) float*)ld(i); }
; __device__ __forceinline__ void swa_item(const KPD& kp, int l, int item, unsigned char* lds, int tid, int lane, int wave) {
;     ...
;     float mrow[3], lrow[3]; f32x4 O[3][4];
; #pragma unroll
;     for (int hh = 0; hh < 3; ++hh) { mrow[hh] = kp.in(I_SINK)[l * 6 + kvh * 3 + hh] * 1.4426950408889634f; lrow[hh] = (fq == 0) ? 1.f : 0.f;
; #pragma unroll
;         for (int dt = 0; dt < 4; ++dt) O[hh][dt] = (f32x4){0.f, 0.f, 0.f, 0.f}; }
;     int nt = 0; int krow[5]; int kmode[5];
; #pragma unroll
;     for (int kt = 0; kt < 5; ++kt) { krow[kt] = 0; kmode[kt] = 0; }
;     int t0 = 0;
;     if (!isctx) {
;         if (qblk > 0) { krow[0] = b * SEQ + (qblk - 1) * 128; kmode[0] = 1; t0 = 1; }
;     }
;     const bool hasprev = !isctx && qblk > 0, hascur = !isctx, hasnext = !isctx && qblk < 63;
;     const int s_prev = 0, s_next = hasprev ? 1 : 0, s_cur = s_next + (hasnext ? 1 : 0), s_c0 = s_cur + (hascur ? 1 : 0), s_c1 = s_c0 + 1;
;     nt = s_c1 + 1;
;     (void)t0; (void)s_prev;
;     auto tile_row = [&](int i) -> int {
;         if (hasprev && i == 0) return b * SEQ + (qblk - 1) * 128;
;         if (hasnext && i == s_next) return b * SEQ + (qblk + 1) * 128;
;         if (hascur && i == s_cur) return b * SEQ + qblk * 128;
;         if (i == s_c0) return MLAT + b * CTXL;
;         return MLAT + b * CTXL + 128; };
;     auto tile_mode = [&](int i) -> int { if (hasprev && i == 0) return 1; if (hasnext && i == s_next) return 2; return 0; };
;     v4u kpre[4], vpre2[4];
;     const int nstage = (nt + 1) >> 1;
;     ...
;     SWA_LOAD_STAGE(0);
.LBB0_368:
	v_add_u32_e32 v38, s13, v177
	v_mad_i64_i32 v[50:51], s[4:5], v38, s33, v[170:171]
	v_add_u32_e32 v38, s13, v176
	v_mad_i64_i32 v[54:55], s[4:5], v38, s33, v[170:171]
	global_load_dwordx4 v[58:61], v[50:51], off offset:3392
	s_nop 0
	global_load_dwordx4 v[50:53], v[50:51], off offset:3136
	s_nop 0
	global_load_dwordx4 v[62:65], v[54:55], off offset:3392
	s_nop 0
	global_load_dwordx4 v[54:57], v[54:55], off offset:3136
	s_mov_b32 s4, 0x3fb8aa3b
	v_mov_b32_e32 v70, v35
	v_mov_b32_e32 v71, v35
	v_mov_b32_e32 v72, v35
	v_mov_b32_e32 v73, v35
	s_waitcnt vmcnt(10)
	v_mul_f32_e32 v181, 0x3fb8aa3b, v68
	s_waitcnt vmcnt(8)
	v_pk_mul_f32 v[172:173], v[66:67], s[4:5] op_sel_hi:[1,0]
	v_sub_f32_e32 v192, 0, v181
	v_sub_f32_e32 v193, 0, v181
	v_sub_f32_e32 v194, 0, v181
	v_sub_f32_e32 v195, 0, v181
	v_sub_f32_e32 v196, 0, v173
	v_sub_f32_e32 v197, 0, v173
	v_sub_f32_e32 v198, 0, v173
	v_sub_f32_e32 v199, 0, v173
	v_sub_f32_e32 v200, 0, v172
	v_sub_f32_e32 v201, 0, v172
	v_sub_f32_e32 v202, 0, v172
	v_sub_f32_e32 v203, 0, v172
	s_add_i32 s4, s19, 3
	s_add_i32 s20, s19, 2
	v_mov_b64_e32 v[66:67], v[70:71]
	v_mov_b64_e32 v[80:81], v[72:73]
	v_mov_b64_e32 v[76:77], v[72:73]
	v_mov_b64_e32 v[84:85], v[72:73]
	v_mov_b64_e32 v[88:89], v[72:73]
	v_mov_b64_e32 v[96:97], v[72:73]
	v_mov_b64_e32 v[92:93], v[72:73]
	v_mov_b64_e32 v[100:101], v[72:73]
	v_mov_b64_e32 v[104:105], v[72:73]
	v_mov_b64_e32 v[112:113], v[72:73]
	v_mov_b64_e32 v[108:109], v[72:73]
	v_ashrrev_i32_e32 v169, 31, v168
	s_lshr_b32 s21, s4, 1
	s_mov_b32 s22, 0
	v_mov_b64_e32 v[68:69], v[72:73]
	v_mov_b64_e32 v[78:79], v[70:71]
	v_mov_b64_e32 v[74:75], v[70:71]
	v_mov_b64_e32 v[82:83], v[70:71]
	v_mov_b64_e32 v[86:87], v[70:71]
	v_mov_b64_e32 v[94:95], v[70:71]
	v_mov_b64_e32 v[90:91], v[70:71]
	v_mov_b64_e32 v[98:99], v[70:71]
	v_mov_b64_e32 v[102:103], v[70:71]
	v_mov_b64_e32 v[110:111], v[70:71]
	v_mov_b64_e32 v[106:107], v[70:71]
	v_mov_b32_e32 v167, v175
	v_mov_b32_e32 v165, v175
	v_mov_b32_e32 v163, v175
	s_mov_b32 s23, s20
	s_branch .LBB0_370

; __device__ __forceinline__ unsigned cvtpk_b(float lo, float hi) { f32x2c_t v = {lo, hi}; bf16x2c_t b = __builtin_convertvector(v, bf16x2c_t); return __builtin_bit_cast(unsigned, b); }
; __device__ __forceinline__ void swa_item(const KPD& kp, int l, int item, unsigned char* lds, int tid, int lane, int wave) {
;     ...
;                 float rs = 0.f; unsigned pw[8];
; #pragma unroll
;                 for (int ct = 0; ct < 4; ++ct) { const float p0 = __builtin_amdgcn_exp2f(S[hh][ct][0] - mnew), p1 = __builtin_amdgcn_exp2f(S[hh][ct][1] - mnew), p2 = __builtin_amdgcn_exp2f(S[hh][ct][2] - mnew), p3 = __builtin_amdgcn_exp2f(S[hh][ct][3] - mnew);
;                     rs += (p0 + p1) + (p2 + p3); pw[2 * ct] = cvtpk_b(p0, p1); pw[2 * ct + 1] = cvtpk_b(p2, p3); }
;                 lrow[hh] += rs; mrow[hh] = mnew;
;                 pf[hh][0] = __builtin_bit_cast(bf16x8, (v4u){pw[0], pw[1], pw[2], pw[3]});
;                 pf[hh][1] = __builtin_bit_cast(bf16x8, (v4u){pw[4], pw[5], pw[6], pw[7]});
;             }
; #pragma unroll
;             for (int c2 = 0; c2 < 2; ++c2)
; #pragma unroll
;                 for (int dt = 0; dt < 4; ++dt) {
;                     const __attribute__((address_space(3))) bf16* vp = (const __attribute__((address_space(3))) bf16*)Vss + (64 * half + 32 * c2 + 4 * fq + q4) * 72 + 16 * dt + 4 * p4;
;                     const v4i16_t lo = __builtin_amdgcn_ds_read_tr16_b64_v4i16((__attribute__((address_space(3))) v4i16_t*)vp);
;                     const v4i16_t hi = __builtin_amdgcn_ds_read_tr16_b64_v4i16((__attribute__((address_space(3))) v4i16_t*)(vp + 16 * 72));
;                     const bf16x8 vf = (bf16x8){lo[0], lo[1], lo[2], lo[3], hi[0], hi[1], hi[2], hi[3]};
; #pragma unroll
;                     for (int hh = 0; hh < 3; ++hh) O[hh][dt] = __builtin_amdgcn_mfma_f32_16x16x32_bf16(vf, pf[hh][c2], O[hh][dt], 0, 0, 0); }
.LBB0_381:
	v_exp_f32_e32 v38, v150
	v_exp_f32_e32 v39, v151
	v_exp_f32_e32 v40, v152
	v_exp_f32_e32 v41, v153
	v_add_f32_e32 v150, v38, v39
	v_add_f32_e32 v151, v40, v41
	v_add_f32_e32 v150, v150, v151
	v_add_f32_e32 v152, 0, v150
	v_cvt_pk_bf16_f32 v150, v38, v39
	v_cvt_pk_bf16_f32 v151, v40, v41
	v_exp_f32_e32 v38, v158
	v_exp_f32_e32 v39, v159
	v_exp_f32_e32 v40, v160
	v_exp_f32_e32 v41, v161
	v_add_f32_e32 v153, v38, v39
	v_add_f32_e32 v158, v40, v41
	v_add_f32_e32 v153, v153, v158
	v_add_f32_e32 v158, v153, v152
	v_cvt_pk_bf16_f32 v152, v38, v39
	v_cvt_pk_bf16_f32 v153, v40, v41
	v_exp_f32_e32 v38, v130
	v_exp_f32_e32 v39, v131
	v_exp_f32_e32 v40, v132
	v_exp_f32_e32 v41, v133
	v_add_f32_e32 v130, v38, v39
	v_add_f32_e32 v131, v40, v41
	v_add_f32_e32 v130, v130, v131
	v_add_f32_e32 v132, v130, v158
	v_cvt_pk_bf16_f32 v130, v38, v39
	v_cvt_pk_bf16_f32 v131, v40, v41
	v_exp_f32_e32 v38, v154
	v_exp_f32_e32 v39, v155
	v_exp_f32_e32 v40, v156
	v_exp_f32_e32 v41, v157
	v_add_f32_e32 v133, v38, v39
	v_add_f32_e32 v154, v40, v41
	v_add_f32_e32 v133, v133, v154
	v_add_f32_e32 v154, v133, v132
	v_cvt_pk_bf16_f32 v132, v38, v39
	v_cvt_pk_bf16_f32 v133, v40, v41
	v_exp_f32_e32 v38, v146
	v_exp_f32_e32 v39, v147
	v_exp_f32_e32 v40, v148
	v_exp_f32_e32 v41, v149
	v_add_f32_e32 v165, v165, v154
	v_add_f32_e32 v146, v38, v39
	v_add_f32_e32 v147, v40, v41
	v_add_f32_e32 v146, v146, v147
	v_add_f32_e32 v148, 0, v146
	v_cvt_pk_bf16_f32 v146, v38, v39
	v_cvt_pk_bf16_f32 v147, v40, v41
	v_exp_f32_e32 v38, v142
	v_exp_f32_e32 v39, v143
	v_exp_f32_e32 v40, v144
	v_exp_f32_e32 v41, v145
	v_add_f32_e32 v142, v38, v39
	v_add_f32_e32 v143, v40, v41
	v_add_f32_e32 v142, v142, v143
	v_add_f32_e32 v142, v142, v148
	v_cvt_pk_bf16_f32 v148, v38, v39
	v_cvt_pk_bf16_f32 v149, v40, v41
	v_exp_f32_e32 v38, v138
	v_exp_f32_e32 v39, v139
	v_exp_f32_e32 v40, v140
	v_exp_f32_e32 v41, v141
	v_add_f32_e32 v138, v38, v39
	v_add_f32_e32 v139, v40, v41
	v_add_f32_e32 v138, v138, v139
	v_add_f32_e32 v140, v138, v142
	v_cvt_pk_bf16_f32 v138, v38, v39
	v_cvt_pk_bf16_f32 v139, v40, v41
	v_exp_f32_e32 v38, v134
	v_exp_f32_e32 v39, v135
	v_exp_f32_e32 v40, v136
	v_exp_f32_e32 v41, v137
	v_add_f32_e32 v134, v38, v39
	v_add_f32_e32 v135, v40, v41
	v_add_f32_e32 v134, v134, v135
	v_add_f32_e32 v134, v134, v140
	v_cvt_pk_bf16_f32 v140, v38, v39
	v_exp_f32_e32 v126, v126
	v_add_f32_e32 v167, v167, v134
	v_exp_f32_e32 v134, v127
	v_exp_f32_e32 v127, v128
	v_exp_f32_e32 v135, v129
	v_exp_f32_e32 v39, v119
	v_cvt_pk_bf16_f32 v141, v40, v41
	v_pk_add_f32 v[128:129], v[126:127], v[134:135]
	v_cvt_pk_bf16_f32 v126, v126, v134
	v_add_f32_e32 v38, v128, v129
	v_add_f32_e32 v137, 0, v38
	v_exp_f32_e32 v114, v114
	v_exp_f32_e32 v128, v115
	v_exp_f32_e32 v115, v116
	v_exp_f32_e32 v129, v117
	v_exp_f32_e32 v38, v118
	v_cvt_pk_bf16_f32 v127, v127, v135
	v_pk_add_f32 v[116:117], v[114:115], v[128:129]
	v_cvt_pk_bf16_f32 v128, v114, v128
	v_pk_add_f32 v[134:135], v[116:117], v[116:117] op_sel_hi:[0,1]
	v_add_f32_e32 v117, v38, v39
	v_cvt_pk_bf16_f32 v114, v38, v39
	v_exp_f32_e32 v116, v122
	v_exp_f32_e32 v118, v123
	v_exp_f32_e32 v40, v120
	v_exp_f32_e32 v41, v121
	v_exp_f32_e32 v134, v124
	v_exp_f32_e32 v136, v125
	v_add_f32_e32 v119, v40, v41
	v_pk_add_f32 v[120:121], v[116:117], v[118:119]
	v_cvt_pk_bf16_f32 v116, v116, v118
	v_pk_add_f32 v[122:123], v[134:135], v[136:137]
	v_cvt_pk_bf16_f32 v129, v115, v129
	v_pk_add_f32 v[120:121], v[120:121], v[122:123]
	v_cvt_pk_bf16_f32 v115, v40, v41
	v_add_f32_e32 v38, v120, v121
	v_add_f32_e32 v163, v163, v38
	v_or_b32_e32 v38, s27, v179
	v_mul_u32_u24_e32 v38, 0x90, v38
	v_add3_u32 v38, v180, s28, v38
	ds_read_b64_tr_b16 v[120:121], v38 offset:20736
	ds_read_b64_tr_b16 v[118:119], v38 offset:18432
	ds_read_b64_tr_b16 v[122:123], v38 offset:18464
	s_waitcnt lgkmcnt(1)
	v_mfma_f32_16x16x32_bf16 v[106:109], v[118:121], v[146:149], v[106:109]
	ds_read_b64_tr_b16 v[124:125], v38 offset:20768
	v_cvt_pk_bf16_f32 v117, v134, v136
	v_mfma_f32_16x16x32_bf16 v[90:93], v[118:121], v[150:153], v[90:93]
	v_mfma_f32_16x16x32_bf16 v[74:77], v[118:121], v[126:129], v[74:77]
	ds_read_b64_tr_b16 v[118:119], v38 offset:18496
	ds_read_b64_tr_b16 v[120:121], v38 offset:20800
	s_waitcnt lgkmcnt(0)
	v_mfma_f32_16x16x32_bf16 v[102:105], v[118:121], v[146:149], v[102:105]
	v_mfma_f32_16x16x32_bf16 v[86:89], v[118:121], v[150:153], v[86:89]
	v_mfma_f32_16x16x32_bf16 v[66:69], v[118:121], v[126:129], v[66:69]
	ds_read_b64_tr_b16 v[118:119], v38 offset:18528
	ds_read_b64_tr_b16 v[120:121], v38 offset:20832
	s_waitcnt lgkmcnt(0)
	v_mfma_f32_16x16x32_bf16 v[98:101], v[118:121], v[146:149], v[98:101]
	v_mfma_f32_16x16x32_bf16 v[82:85], v[118:121], v[150:153], v[82:85]
	v_mfma_f32_16x16x32_bf16 v[70:73], v[118:121], v[126:129], v[70:73]
	ds_read_b64_tr_b16 v[118:119], v38 offset:23040
	ds_read_b64_tr_b16 v[120:121], v38 offset:25344
	s_waitcnt lgkmcnt(0)
	v_mfma_f32_16x16x32_bf16 v[106:109], v[118:121], v[138:141], v[106:109]
	v_mfma_f32_16x16x32_bf16 v[90:93], v[118:121], v[130:133], v[90:93]
	v_mfma_f32_16x16x32_bf16 v[74:77], v[118:121], v[114:117], v[74:77]
	ds_read_b64_tr_b16 v[118:119], v38 offset:23072
	ds_read_b64_tr_b16 v[120:121], v38 offset:25376
	v_mfma_f32_16x16x32_bf16 v[110:113], v[122:125], v[146:149], v[110:113]
	v_mfma_f32_16x16x32_bf16 v[94:97], v[122:125], v[150:153], v[94:97]
	v_mfma_f32_16x16x32_bf16 v[78:81], v[122:125], v[126:129], v[78:81]
	s_waitcnt lgkmcnt(0)
	v_mfma_f32_16x16x32_bf16 v[110:113], v[118:121], v[138:141], v[110:113]
	v_mfma_f32_16x16x32_bf16 v[94:97], v[118:121], v[130:133], v[94:97]
	v_mfma_f32_16x16x32_bf16 v[78:81], v[118:121], v[114:117], v[78:81]
	ds_read_b64_tr_b16 v[118:119], v38 offset:23104
	ds_read_b64_tr_b16 v[120:121], v38 offset:25408
	s_waitcnt lgkmcnt(0)
	v_mfma_f32_16x16x32_bf16 v[102:105], v[118:121], v[138:141], v[102:105]
	v_mfma_f32_16x16x32_bf16 v[86:89], v[118:121], v[130:133], v[86:89]
	v_mfma_f32_16x16x32_bf16 v[66:69], v[118:121], v[114:117], v[66:69]
	ds_read_b64_tr_b16 v[118:119], v38 offset:23136
	ds_read_b64_tr_b16 v[120:121], v38 offset:25440
	s_waitcnt lgkmcnt(0)
	v_mfma_f32_16x16x32_bf16 v[98:101], v[118:121], v[138:141], v[98:101]
	v_mfma_f32_16x16x32_bf16 v[82:85], v[118:121], v[130:133], v[82:85]
	v_mfma_f32_16x16x32_bf16 v[70:73], v[118:121], v[114:117], v[70:73]

; __device__ __forceinline__ void swa_item(const KPD& kp, int l, int item, unsigned char* lds, int tid, int lane, int wave) {
;     ...
;         for (int h2 = 0; h2 < 2 * ntl; ++h2) {
;             const int slot = h2 >> 1, half = h2 & 1, mode = tile_mode(ta + slot);
;             const bf16* Ktt = Kt + slot * 18432; const bf16* Vss = Vs + slot * 18432;
;             if ((mode == 1 && half == 0 && wave >= 4) || (mode == 2 && half == 1 && wave <= 3)) continue;
;             f32x4 S[3][4];
; #pragma unroll
;             for (int ct = 0; ct < 4; ++ct) {
; #pragma unroll
;                 for (int hh = 0; hh < 3; ++hh) S[hh][ct] = (f32x4){0.f, 0.f, 0.f, 0.f};
; #pragma unroll
;                 for (int ks = 0; ks < 2; ++ks) { const bf16x8 kf = *(const bf16x8*)(Ktt + (64 * half + 16 * ct + fr) * 72 + 32 * ks + 8 * fq);
; #pragma unroll
;                     for (int hh = 0; hh < 3; ++hh) S[hh][ct] = __builtin_amdgcn_mfma_f32_16x16x32_bf16(kf, qf[hh][ks], S[hh][ct], 0, 0, 0); } }
;             if (mode != 0) {
;                 const int qi = 16 * wave + fr;
; #pragma unroll
;                 for (int ct = 0; ct < 4; ++ct)
; #pragma unroll
;                     for (int r = 0; r < 4; ++r) { const int key = 64 * half + 16 * ct + 4 * fq + r;
;                         const bool bad = (mode == 1) ? (key < qi) : (key > qi);
;                         if (bad) { S[0][ct][r] = -1e30f; S[1][ct][r] = -1e30f; S[2][ct][r] = -1e30f; } }
;             }
.LBB0_383:
	s_lshr_b32 s27, s26, 1
	s_and_b32 s28, s26, 1
	s_add_i32 s12, s27, s24
	s_cmp_eq_u32 s12, 0
	s_cselect_b64 s[4:5], -1, 0
	s_and_b64 s[4:5], s[8:9], s[4:5]
	s_cmp_eq_u32 s28, 0
	s_cselect_b64 s[30:31], -1, 0
	s_and_b64 s[30:31], s[0:1], s[30:31]
	s_and_b64 s[30:31], s[30:31], s[4:5]
	s_and_b64 vcc, exec, s[30:31]
	s_cbranch_vccnz .LBB0_382
	s_cmp_eq_u32 s12, s17
	s_cselect_b64 s[12:13], -1, 0
	s_and_b64 s[12:13], s[10:11], s[12:13]
	s_xor_b64 s[30:31], s[4:5], -1
	s_cmp_lg_u32 s28, 0
	s_cselect_b64 s[34:35], -1, 0
	s_and_b64 s[30:31], s[34:35], s[30:31]
	s_and_b64 s[30:31], s[2:3], s[30:31]
	s_and_b64 s[30:31], s[12:13], s[30:31]
	s_and_b64 vcc, exec, s[30:31]
	s_cbranch_vccnz .LBB0_382
	s_mul_i32 s29, s27, 0x4800
	s_lshl_b32 s27, s28, 6
	v_or_b32_e32 v38, s27, v37
	s_lshl_b32 s28, s29, 1
	v_mul_u32_u24_e32 v38, 0x90, v38
	v_add3_u32 v38, v178, s28, v38
	ds_read_b128 v[114:117], v38
	ds_read_b128 v[118:121], v38 offset:64
	s_or_b64 s[12:13], s[4:5], s[12:13]
	s_waitcnt lgkmcnt(1)
	v_mfma_f32_16x16x32_bf16 v[122:125], v[114:117], v[2:5], v[192:195]
	s_andn2_b64 vcc, exec, s[12:13]
	v_mfma_f32_16x16x32_bf16 v[126:129], v[114:117], v[10:13], v[196:199]
	v_mfma_f32_16x16x32_bf16 v[114:117], v[114:117], v[18:21], v[200:203]
	s_waitcnt lgkmcnt(0)
	v_mfma_f32_16x16x32_bf16 v[146:149], v[118:121], v[6:9], v[122:125]
	v_mfma_f32_16x16x32_bf16 v[150:153], v[118:121], v[14:17], v[126:129]
	v_mfma_f32_16x16x32_bf16 v[126:129], v[118:121], v[22:25], v[114:117]
	s_nop 3
	ds_read_b128 v[114:117], v38 offset:2304
	ds_read_b128 v[118:121], v38 offset:2368
	s_waitcnt lgkmcnt(1)
	v_mfma_f32_16x16x32_bf16 v[122:125], v[114:117], v[2:5], v[192:195]
	v_mfma_f32_16x16x32_bf16 v[130:133], v[114:117], v[10:13], v[196:199]
	v_mfma_f32_16x16x32_bf16 v[114:117], v[114:117], v[18:21], v[200:203]
	s_waitcnt lgkmcnt(0)
	v_mfma_f32_16x16x32_bf16 v[142:145], v[118:121], v[6:9], v[122:125]
	v_mfma_f32_16x16x32_bf16 v[158:161], v[118:121], v[14:17], v[130:133]
	v_mfma_f32_16x16x32_bf16 v[114:117], v[118:121], v[22:25], v[114:117]
	ds_read_b128 v[118:121], v38 offset:4608
	s_nop 0
	ds_read_b128 v[122:125], v38 offset:4672
	s_waitcnt lgkmcnt(1)
	v_mfma_f32_16x16x32_bf16 v[130:133], v[118:121], v[2:5], v[192:195]
	v_mfma_f32_16x16x32_bf16 v[134:137], v[118:121], v[10:13], v[196:199]
	v_mfma_f32_16x16x32_bf16 v[118:121], v[118:121], v[18:21], v[200:203]
	s_waitcnt lgkmcnt(0)
	v_mfma_f32_16x16x32_bf16 v[138:141], v[122:125], v[6:9], v[130:133]
	v_mfma_f32_16x16x32_bf16 v[130:133], v[122:125], v[14:17], v[134:137]
	v_mfma_f32_16x16x32_bf16 v[118:121], v[122:125], v[22:25], v[118:121]
	ds_read_b128 v[122:125], v38 offset:6912
	ds_read_b128 v[186:189], v38 offset:6976
	s_waitcnt lgkmcnt(1)
	v_mfma_f32_16x16x32_bf16 v[134:137], v[122:125], v[2:5], v[192:195]
	v_mfma_f32_16x16x32_bf16 v[154:157], v[122:125], v[10:13], v[196:199]
	v_mfma_f32_16x16x32_bf16 v[122:125], v[122:125], v[18:21], v[200:203]
	s_waitcnt lgkmcnt(0)
	v_mfma_f32_16x16x32_bf16 v[134:137], v[186:189], v[6:9], v[134:137]
	v_mfma_f32_16x16x32_bf16 v[154:157], v[186:189], v[14:17], v[154:157]
	v_mfma_f32_16x16x32_bf16 v[122:125], v[186:189], v[22:25], v[122:125]
	s_cbranch_vccnz .LBB0_387
	v_or_b32_e32 v38, s27, v36
	v_mov_b32_e32 v186, s58
	v_mov_b32_e32 v188, s58
	v_mov_b32_e32 v190, s58
	v_sub_u32_e32 v39, v174, v38
	s_and_b64 vcc, exec, s[4:5]
	s_cbranch_vccz .Lswa_mask_next
	v_cmp_lt_i32_e64 s[30:31], 0, v39
	v_cmp_lt_i32_e64 s[34:35], 1, v39
	v_cmp_lt_i32_e64 s[36:37], 2, v39
	v_cndmask_b32_e64 v126, v126, v190, s[30:31]
	v_cndmask_b32_e64 v150, v150, v188, s[30:31]
	v_cndmask_b32_e64 v146, v146, v186, s[30:31]
	v_cmp_lt_i32_e64 s[40:41], 3, v39
	v_cndmask_b32_e64 v127, v127, v224, s[34:35]
	v_cndmask_b32_e64 v151, v151, v224, s[34:35]
	v_cndmask_b32_e64 v147, v147, v224, s[34:35]
	v_cmp_lt_i32_e64 s[30:31], 16, v39
	v_cndmask_b32_e64 v128, v128, v224, s[36:37]
	v_cndmask_b32_e64 v152, v152, v224, s[36:37]
	v_cndmask_b32_e64 v148, v148, v224, s[36:37]
	v_cmp_lt_i32_e64 s[34:35], 17, v39
	v_cndmask_b32_e64 v129, v129, v224, s[40:41]
	v_cndmask_b32_e64 v153, v153, v224, s[40:41]
	v_cndmask_b32_e64 v149, v149, v224, s[40:41]
	v_cmp_lt_i32_e64 s[36:37], 18, v39
	v_cndmask_b32_e64 v114, v114, v190, s[30:31]
	v_cndmask_b32_e64 v158, v158, v188, s[30:31]
	v_cndmask_b32_e64 v142, v142, v186, s[30:31]
	v_cmp_lt_i32_e64 s[40:41], 19, v39
	v_cndmask_b32_e64 v115, v115, v224, s[34:35]
	v_cndmask_b32_e64 v159, v159, v224, s[34:35]
	v_cndmask_b32_e64 v143, v143, v224, s[34:35]
	v_cmp_lt_i32_e64 s[30:31], 32, v39
	v_cndmask_b32_e64 v116, v116, v224, s[36:37]
	v_cndmask_b32_e64 v160, v160, v224, s[36:37]
	v_cndmask_b32_e64 v144, v144, v224, s[36:37]
	v_cmp_lt_i32_e64 s[34:35], 33, v39
	v_cndmask_b32_e64 v117, v117, v224, s[40:41]
	v_cndmask_b32_e64 v161, v161, v224, s[40:41]
	v_cndmask_b32_e64 v145, v145, v224, s[40:41]
	v_cmp_lt_i32_e64 s[36:37], 34, v39
	v_cndmask_b32_e64 v118, v118, v190, s[30:31]
	v_cndmask_b32_e64 v130, v130, v188, s[30:31]
	v_cndmask_b32_e64 v138, v138, v186, s[30:31]
	v_cmp_lt_i32_e64 s[40:41], 35, v39
	v_cndmask_b32_e64 v119, v119, v224, s[34:35]
	v_cndmask_b32_e64 v131, v131, v224, s[34:35]
	v_cndmask_b32_e64 v139, v139, v224, s[34:35]
	v_cmp_lt_i32_e64 s[30:31], 48, v39
	v_cndmask_b32_e64 v120, v120, v224, s[36:37]
	v_cndmask_b32_e64 v132, v132, v224, s[36:37]
	v_cndmask_b32_e64 v140, v140, v224, s[36:37]
	v_cmp_lt_i32_e64 s[34:35], 49, v39
	v_cndmask_b32_e64 v121, v121, v224, s[40:41]
	v_cndmask_b32_e64 v133, v133, v224, s[40:41]
	v_cndmask_b32_e64 v141, v141, v224, s[40:41]
	v_cmp_lt_i32_e64 s[36:37], 50, v39
	v_cndmask_b32_e64 v122, v122, v190, s[30:31]
	v_cndmask_b32_e64 v154, v154, v188, s[30:31]
	v_cndmask_b32_e64 v134, v134, v186, s[30:31]
	v_cmp_lt_i32_e64 s[40:41], 51, v39
	v_cndmask_b32_e64 v123, v123, v224, s[34:35]
	v_cndmask_b32_e64 v155, v155, v224, s[34:35]
	v_cndmask_b32_e64 v135, v135, v224, s[34:35]
	v_cndmask_b32_e64 v124, v124, v224, s[36:37]
	v_cndmask_b32_e64 v156, v156, v224, s[36:37]
	v_cndmask_b32_e64 v136, v136, v224, s[36:37]
	v_cndmask_b32_e64 v125, v125, v224, s[40:41]
	v_cndmask_b32_e64 v157, v157, v224, s[40:41]
	v_cndmask_b32_e64 v137, v137, v224, s[40:41]
	s_branch .LBB0_387

; __device__ __forceinline__ float xor16_32_max(float v) { float a = v, b = v; swap16(a, b); v = fmaxf(a, b); a = v; b = v; swap32(a, b); return fmaxf(a, b); }
; __device__ __forceinline__ unsigned cvtpk_b(float lo, float hi) { f32x2c_t v = {lo, hi}; bf16x2c_t b = __builtin_convertvector(v, bf16x2c_t); return __builtin_bit_cast(unsigned, b); }
; __device__ __forceinline__ void swa_item(const KPD& kp, int l, int item, unsigned char* lds, int tid, int lane, int wave) {
;     ...
;             for (int hh = 0; hh < 3; ++hh) {
;                 float mx = fmaxf(fmaxf(S[hh][0][0], S[hh][0][1]), fmaxf(S[hh][0][2], S[hh][0][3]));
; #pragma unroll
;                 for (int ct = 1; ct < 4; ++ct) mx = fmaxf(mx, fmaxf(fmaxf(S[hh][ct][0], S[hh][ct][1]), fmaxf(S[hh][ct][2], S[hh][ct][3])));
;                 mx = pg8::xor16_32_max(mx);
;                 float mnew = mrow[hh];
;                 const bool resc = __builtin_amdgcn_ballot_w64(mx > mrow[hh] + 8.0f) != 0ull;
;                 if (resc) { mnew = fmaxf(mrow[hh], mx); const float alpha = __builtin_amdgcn_exp2f(mrow[hh] - mnew); lrow[hh] *= alpha;
; #pragma unroll
;                     for (int dt = 0; dt < 4; ++dt) O[hh][dt] *= alpha; }
;                 float rs = 0.f; unsigned pw[8];
; #pragma unroll
;                 for (int ct = 0; ct < 4; ++ct) { const float p0 = __builtin_amdgcn_exp2f(S[hh][ct][0] - mnew), p1 = __builtin_amdgcn_exp2f(S[hh][ct][1] - mnew), p2 = __builtin_amdgcn_exp2f(S[hh][ct][2] - mnew), p3 = __builtin_amdgcn_exp2f(S[hh][ct][3] - mnew);
;                     rs += (p0 + p1) + (p2 + p3); pw[2 * ct] = cvtpk_b(p0, p1); pw[2 * ct + 1] = cvtpk_b(p2, p3); }
;                 lrow[hh] += rs; mrow[hh] = mnew;
;                 pf[hh][0] = __builtin_bit_cast(bf16x8, (v4u){pw[0], pw[1], pw[2], pw[3]});
;                 pf[hh][1] = __builtin_bit_cast(bf16x8, (v4u){pw[4], pw[5], pw[6], pw[7]});
;             }
.LBB0_387:
	v_max3_f32 v38, v138, v139, v140
	v_max3_f32 v39, v141, v142, v143
	v_max3_f32 v40, v144, v145, v146
	v_max3_f32 v41, v147, v148, v149
	v_max3_f32 v38, v38, v39, v40
	s_nop 1
	v_max3_f32 v38, v38, v41, v134
	v_max3_f32 v38, v38, v135, v136
	v_max_f32_e32 v38, v38, v137
	v_mov_b32_e32 v39, v38
	s_nop 1
	v_permlane16_swap_b32 v39, v38
	s_nop 0
	v_max_f32_e32 v38, v39, v38
	v_mov_b32_e32 v39, v38
	s_nop 1
	v_permlane32_swap_b32 v39, v38
	s_nop 0
	v_max_f32_e32 v186, v39, v38
	v_mov_b32_e32 v38, 0x41000000
	v_cmp_gt_f32_e32 vcc, v186, v38
	s_cbranch_vccz .LBB0_389
	v_max_f32_e32 v38, 0, v186
	v_sub_f32_e32 v39, 0, v38
	v_add_f32_e32 v40, v181, v38
	v_exp_f32_e32 v186, v39
	s_nop 0
	v_mul_f32_e32 v167, v167, v186
	v_pk_mul_f32 v[108:109], v[108:109], v[186:187] op_sel_hi:[1,0]
	v_pk_mul_f32 v[106:107], v[106:107], v[186:187] op_sel_hi:[1,0]
	v_pk_mul_f32 v[112:113], v[112:113], v[186:187] op_sel_hi:[1,0]
	v_pk_mul_f32 v[110:111], v[110:111], v[186:187] op_sel_hi:[1,0]
	v_pk_mul_f32 v[104:105], v[104:105], v[186:187] op_sel_hi:[1,0]
	v_pk_mul_f32 v[102:103], v[102:103], v[186:187] op_sel_hi:[1,0]
	v_pk_mul_f32 v[100:101], v[100:101], v[186:187] op_sel_hi:[1,0]
	v_pk_mul_f32 v[98:99], v[98:99], v[186:187] op_sel_hi:[1,0]
	v_sub_f32_e32 v134, v134, v38
	v_sub_f32_e32 v135, v135, v38
	v_sub_f32_e32 v136, v136, v38
	v_sub_f32_e32 v137, v137, v38
	v_sub_f32_e32 v138, v138, v38
	v_sub_f32_e32 v139, v139, v38
	v_sub_f32_e32 v140, v140, v38
	v_sub_f32_e32 v141, v141, v38
	v_sub_f32_e32 v142, v142, v38
	v_sub_f32_e32 v143, v143, v38
	v_sub_f32_e32 v144, v144, v38
	v_sub_f32_e32 v145, v145, v38
	v_sub_f32_e32 v146, v146, v38
	v_sub_f32_e32 v147, v147, v38
	v_sub_f32_e32 v148, v148, v38
	v_sub_f32_e32 v149, v149, v38
	v_sub_f32_e32 v192, v192, v38
	v_sub_f32_e32 v193, v193, v38
	v_sub_f32_e32 v194, v194, v38
	v_sub_f32_e32 v195, v195, v38
	v_mov_b32_e32 v181, v40
.LBB0_389:
	v_max3_f32 v38, v130, v131, v132
	v_max3_f32 v39, v133, v150, v151
	v_max3_f32 v40, v152, v153, v158
	v_max3_f32 v41, v159, v160, v161
	v_max3_f32 v38, v38, v39, v40
	s_nop 1
	v_max3_f32 v38, v38, v41, v154
	v_max3_f32 v38, v38, v155, v156
	v_max_f32_e32 v38, v38, v157
	v_mov_b32_e32 v39, v38
	s_nop 1
	v_permlane16_swap_b32 v39, v38
	s_nop 0
	v_max_f32_e32 v38, v39, v38
	v_mov_b32_e32 v39, v38
	s_nop 1
	v_permlane32_swap_b32 v39, v38
	s_nop 0
	v_max_f32_e32 v186, v39, v38
	v_mov_b32_e32 v38, 0x41000000
	v_cmp_gt_f32_e32 vcc, v186, v38
	s_cbranch_vccz .LBB0_391
	v_max_f32_e32 v38, 0, v186
	v_sub_f32_e32 v39, 0, v38
	v_add_f32_e32 v40, v173, v38
	v_exp_f32_e32 v186, v39
	s_nop 0
	v_mul_f32_e32 v165, v165, v186
	v_pk_mul_f32 v[92:93], v[92:93], v[186:187] op_sel_hi:[1,0]
	v_pk_mul_f32 v[90:91], v[90:91], v[186:187] op_sel_hi:[1,0]
	v_pk_mul_f32 v[96:97], v[96:97], v[186:187] op_sel_hi:[1,0]
	v_pk_mul_f32 v[94:95], v[94:95], v[186:187] op_sel_hi:[1,0]
	v_pk_mul_f32 v[88:89], v[88:89], v[186:187] op_sel_hi:[1,0]
	v_pk_mul_f32 v[86:87], v[86:87], v[186:187] op_sel_hi:[1,0]
	v_pk_mul_f32 v[84:85], v[84:85], v[186:187] op_sel_hi:[1,0]
	v_pk_mul_f32 v[82:83], v[82:83], v[186:187] op_sel_hi:[1,0]
	v_sub_f32_e32 v130, v130, v38
	v_sub_f32_e32 v131, v131, v38
	v_sub_f32_e32 v132, v132, v38
	v_sub_f32_e32 v133, v133, v38
	v_sub_f32_e32 v150, v150, v38
	v_sub_f32_e32 v151, v151, v38
	v_sub_f32_e32 v152, v152, v38
	v_sub_f32_e32 v153, v153, v38
	v_sub_f32_e32 v154, v154, v38
	v_sub_f32_e32 v155, v155, v38
	v_sub_f32_e32 v156, v156, v38
	v_sub_f32_e32 v157, v157, v38
	v_sub_f32_e32 v158, v158, v38
	v_sub_f32_e32 v159, v159, v38
	v_sub_f32_e32 v160, v160, v38
	v_sub_f32_e32 v161, v161, v38
	v_sub_f32_e32 v196, v196, v38
	v_sub_f32_e32 v197, v197, v38
	v_sub_f32_e32 v198, v198, v38
	v_sub_f32_e32 v199, v199, v38
	v_mov_b32_e32 v173, v40
.LBB0_391:
	v_max3_f32 v38, v114, v115, v116
	v_max3_f32 v39, v117, v118, v119
	v_max3_f32 v40, v120, v121, v126
	v_max3_f32 v41, v127, v128, v129
	v_max3_f32 v38, v38, v39, v40
	s_nop 1
	v_max3_f32 v38, v38, v41, v122
	v_max3_f32 v38, v38, v123, v124
	v_max_f32_e32 v38, v38, v125
	v_mov_b32_e32 v39, v38
	s_nop 1
	v_permlane16_swap_b32 v39, v38
	s_nop 0
	v_max_f32_e32 v38, v39, v38
	v_mov_b32_e32 v39, v38
	s_nop 1
	v_permlane32_swap_b32 v39, v38
	s_nop 0
	v_max_f32_e32 v186, v39, v38
	v_mov_b32_e32 v38, 0x41000000
	v_cmp_gt_f32_e32 vcc, v186, v38
	s_cbranch_vccz .LBB0_381
	v_max_f32_e32 v38, 0, v186
	v_sub_f32_e32 v39, 0, v38
	v_add_f32_e32 v40, v172, v38
	v_exp_f32_e32 v172, v39
	s_nop 0
	v_mul_f32_e32 v163, v163, v172
	v_pk_mul_f32 v[76:77], v[76:77], v[172:173] op_sel_hi:[1,0]
	v_pk_mul_f32 v[74:75], v[74:75], v[172:173] op_sel_hi:[1,0]
	v_pk_mul_f32 v[80:81], v[80:81], v[172:173] op_sel_hi:[1,0]
	v_pk_mul_f32 v[78:79], v[78:79], v[172:173] op_sel_hi:[1,0]
	v_pk_mul_f32 v[68:69], v[68:69], v[172:173] op_sel_hi:[1,0]
	v_pk_mul_f32 v[66:67], v[66:67], v[172:173] op_sel_hi:[1,0]
	v_pk_mul_f32 v[72:73], v[72:73], v[172:173] op_sel_hi:[1,0]
	v_pk_mul_f32 v[70:71], v[70:71], v[172:173] op_sel_hi:[1,0]
	v_sub_f32_e32 v114, v114, v38
	v_sub_f32_e32 v115, v115, v38
	v_sub_f32_e32 v116, v116, v38
	v_sub_f32_e32 v117, v117, v38
	v_sub_f32_e32 v118, v118, v38
	v_sub_f32_e32 v119, v119, v38
	v_sub_f32_e32 v120, v120, v38
	v_sub_f32_e32 v121, v121, v38
	v_sub_f32_e32 v122, v122, v38
	v_sub_f32_e32 v123, v123, v38
	v_sub_f32_e32 v124, v124, v38
	v_sub_f32_e32 v125, v125, v38
	v_sub_f32_e32 v126, v126, v38
	v_sub_f32_e32 v127, v127, v38
	v_sub_f32_e32 v128, v128, v38
	v_sub_f32_e32 v129, v129, v38
	v_sub_f32_e32 v200, v200, v38
	v_sub_f32_e32 v201, v201, v38
	v_sub_f32_e32 v202, v202, v38
	v_sub_f32_e32 v203, v203, v38
	v_mov_b32_e32 v172, v40
	s_branch .LBB0_381
